# NSA compress items software-pipelined (3-deep load ring, same math order) + P4 unit order remap
# baseline (speedup 1.0000x reference)
; DI unsigned cvtpk(float lo, float hi) { f32x2_t v = {lo, hi}; bf16x2_t b = __builtin_convertvector(v, bf16x2_t); return __builtin_bit_cast(unsigned, b); }
; DI void unpack8(const u32x4 w, float (&v)[8]) { v[0] = bflo(w.x); v[1] = bfhi(w.x); v[2] = bflo(w.y); v[3] = bfhi(w.y); v[4] = bflo(w.z); v[5] = bfhi(w.z); v[6] = bflo(w.w); v[7] = bfhi(w.w); }
; #define MFMA32(a, b, c) __builtin_amdgcn_mfma_f32_32x32x16_bf16((a), (b), (c), 0, 0, 0)
; DI void prep_compress_item(const Params& P, int l, int it, LAS unsigned char* lds, int wave, int lane) {
;     ...
;     for (int jj = 0; jj < 4; ++jj) {
;         const int j = 4 * wave + jj;
;         int tok = 16 * n + j; tok = tok > SEQ - 1 ? SEQ - 1 : tok;
;         const bf16_t* xp = hb + (size_t)(b * SEQ + tok) * NIN + col + 8 * h;
; #pragma unroll
;         for (int ds = 0; ds < 4; ++ds) {
;             float v[8]; unpack8(*(const u32x4*)(xp + 16 * ds), v);
;             const f32x4 p0 = *(const f32x4*)(pe + j * 64 + 16 * ds + 8 * h), p1 = *(const f32x4*)(pe + j * 64 + 16 * ds + 8 * h + 4);
;             u32x4 w; w.x = cvtpk(v[0] + p0[0], v[1] + p0[1]); w.y = cvtpk(v[2] + p0[2], v[3] + p0[3]); w.z = cvtpk(v[4] + p1[0], v[5] + p1[1]); w.w = cvtpk(v[6] + p1[2], v[7] + p1[3]);
;             const bf16x8 bfrag = __builtin_bit_cast(bf16x8, w);
;             const int k0 = j * 64 + 16 * ds + 8 * h;
;             const bf16x8 a0 = *(const bf16x8*)(cw + (size_t)r * 2048 + k0), a1 = *(const bf16x8*)(cw + (size_t)(32 + r) * 2048 + k0);
;             acc[0] = MFMA32(a0, bfrag, acc[0]); acc[1] = MFMA32(a1, bfrag, acc[1]);
.LBB0_330:
	s_and_b32 s10, s55, 1
	s_or_b32 s22, s10, s27
	s_ashr_i32 s56, s55, 4
	s_lshl_b64 s[0:1], s[22:23], 18
	s_lshl_b64 s[58:59], s[22:23], 13
	s_and_b32 s24, s45, 0xe0
	v_readlane_b32 s11, v254, 5
	s_add_u32 s60, s11, s0
	v_readlane_b32 s0, v254, 6
	s_addc_u32 s61, s0, s1
	s_cmp_eq_u32 s10, 0
	s_cselect_b64 s[0:1], -1, 0
	v_or_b32_e32 v49, s24, v88
	s_and_b64 s[10:11], s[0:1], exec
	v_lshlrev_b32_e32 v94, 4, v49
	s_movk_i32 s10, 0x1400
	v_add_u32_e32 v0, s34, v94
	s_cselect_b32 s22, s10, 0x1480
	s_lshl_b32 s10, s56, 12
	v_min_i32_e32 v0, 0xfff, v0
	v_lshl_add_u64 v[54:55], v[32:33], 0, s[22:23]
	v_add_u32_e32 v0, s10, v0
	v_lshl_add_u64 v[56:57], v[34:35], 0, s[58:59]
	v_mov_b32_e32 v39, v169
	v_lshl_add_u64 v[50:51], s[60:61], 0, v[168:169]
	v_lshl_add_u64 v[52:53], s[60:61], 0, v[38:39]
	s_andn2_b64 vcc, exec, s[50:51]
	v_add_u32_e32 v74, s34, v94
	v_min_i32_e32 v74, 0xfff, v74
	v_add_u32_e32 v74, s10, v74
	v_mad_i64_i32 v[66:67], s[58:59], v74, s82, v[54:55]
	v_lshl_add_u64 v[68:69], s[38:39], 2, v[56:57]
	v_lshl_add_u64 v[70:71], v[50:51], 0, v[40:41]
	v_lshl_add_u64 v[72:73], v[52:53], 0, v[40:41]
	global_load_dwordx4 v[132:135], v[66:67], off
	global_load_dwordx4 v[136:139], v[68:69], off
	global_load_dwordx4 v[140:143], v[68:69], off offset:16
	global_load_dwordx4 v[144:147], v[70:71], off
	global_load_dwordx4 v[148:151], v[72:73], off
	global_load_dwordx4 v[152:155], v[66:67], off offset:32
	global_load_dwordx4 v[156:159], v[68:69], off offset:64
	global_load_dwordx4 v[220:223], v[68:69], off offset:80
	global_load_dwordx4 v[226:229], v[70:71], off offset:32
	global_load_dwordx4 v[230:233], v[72:73], off offset:32
	global_load_dwordx4 v[234:237], v[66:67], off offset:64
	global_load_dwordx4 v[238:241], v[68:69], off offset:128
	global_load_dwordx4 v[242:245], v[68:69], off offset:144
	global_load_dwordx4 v[246:249], v[70:71], off offset:64
	global_load_dwordx4 v[58:61], v[72:73], off offset:64
	s_waitcnt vmcnt(12)
	v_lshlrev_b32_e32 v62, 16, v132
	v_and_b32_e32 v63, 0xffff0000, v132
	v_lshlrev_b32_e32 v64, 16, v133
	v_and_b32_e32 v65, 0xffff0000, v133
	v_pk_add_f32 v[62:63], v[136:137], v[62:63]
	v_pk_add_f32 v[64:65], v[138:139], v[64:65]
	s_nop 0
	v_cvt_pk_bf16_f32 v132, v62, v63
	v_cvt_pk_bf16_f32 v133, v64, v65
	v_lshlrev_b32_e32 v62, 16, v134
	v_and_b32_e32 v63, 0xffff0000, v134
	v_lshlrev_b32_e32 v64, 16, v135
	v_and_b32_e32 v65, 0xffff0000, v135
	v_pk_add_f32 v[62:63], v[140:141], v[62:63]
	v_pk_add_f32 v[64:65], v[142:143], v[64:65]
	s_nop 0
	v_cvt_pk_bf16_f32 v134, v62, v63
	v_cvt_pk_bf16_f32 v135, v64, v65
	s_waitcnt vmcnt(10)
	s_nop 1
	v_mfma_f32_32x32x16_bf16 v[16:31], v[144:147], v[132:135], 0
	v_mfma_f32_32x32x16_bf16 v[0:15], v[148:151], v[132:135], 0
	global_load_dwordx4 v[132:135], v[66:67], off offset:96
	global_load_dwordx4 v[136:139], v[68:69], off offset:192
	global_load_dwordx4 v[140:143], v[68:69], off offset:208
	global_load_dwordx4 v[144:147], v[70:71], off offset:96
	global_load_dwordx4 v[148:151], v[72:73], off offset:96
	s_waitcnt vmcnt(12)
	v_lshlrev_b32_e32 v62, 16, v152
	v_and_b32_e32 v63, 0xffff0000, v152
	v_lshlrev_b32_e32 v64, 16, v153
	v_and_b32_e32 v65, 0xffff0000, v153
	v_pk_add_f32 v[62:63], v[156:157], v[62:63]
	v_pk_add_f32 v[64:65], v[158:159], v[64:65]
	s_nop 0
	v_cvt_pk_bf16_f32 v152, v62, v63
	v_cvt_pk_bf16_f32 v153, v64, v65
	v_lshlrev_b32_e32 v62, 16, v154
	v_and_b32_e32 v63, 0xffff0000, v154
	v_lshlrev_b32_e32 v64, 16, v155
	v_and_b32_e32 v65, 0xffff0000, v155
	v_pk_add_f32 v[62:63], v[220:221], v[62:63]
	v_pk_add_f32 v[64:65], v[222:223], v[64:65]
	s_nop 0
	v_cvt_pk_bf16_f32 v154, v62, v63
	v_cvt_pk_bf16_f32 v155, v64, v65
	s_waitcnt vmcnt(10)
	s_nop 1
	v_mfma_f32_32x32x16_bf16 v[16:31], v[226:229], v[152:155], v[16:31]
	v_mfma_f32_32x32x16_bf16 v[0:15], v[230:233], v[152:155], v[0:15]
	v_add_u32_e32 v74, s35, v94
	v_min_i32_e32 v74, 0xfff, v74
	v_add_u32_e32 v74, s10, v74
	v_mad_i64_i32 v[66:67], s[58:59], v74, s82, v[54:55]
	v_lshl_add_u64 v[68:69], s[40:41], 2, v[56:57]
	v_lshl_add_u64 v[70:71], v[50:51], 0, v[42:43]
	v_lshl_add_u64 v[72:73], v[52:53], 0, v[42:43]
	global_load_dwordx4 v[152:155], v[66:67], off
	global_load_dwordx4 v[156:159], v[68:69], off
	global_load_dwordx4 v[220:223], v[68:69], off offset:16
	global_load_dwordx4 v[226:229], v[70:71], off
	global_load_dwordx4 v[230:233], v[72:73], off
	s_waitcnt vmcnt(12)
	v_lshlrev_b32_e32 v62, 16, v234
	v_and_b32_e32 v63, 0xffff0000, v234
	v_lshlrev_b32_e32 v64, 16, v235
	v_and_b32_e32 v65, 0xffff0000, v235
	v_pk_add_f32 v[62:63], v[238:239], v[62:63]
	v_pk_add_f32 v[64:65], v[240:241], v[64:65]
	s_nop 0
	v_cvt_pk_bf16_f32 v234, v62, v63
	v_cvt_pk_bf16_f32 v235, v64, v65
	v_lshlrev_b32_e32 v62, 16, v236
	v_and_b32_e32 v63, 0xffff0000, v236
	v_lshlrev_b32_e32 v64, 16, v237
	v_and_b32_e32 v65, 0xffff0000, v237
	v_pk_add_f32 v[62:63], v[242:243], v[62:63]
	v_pk_add_f32 v[64:65], v[244:245], v[64:65]
	s_nop 0
	v_cvt_pk_bf16_f32 v236, v62, v63
	v_cvt_pk_bf16_f32 v237, v64, v65
	s_waitcnt vmcnt(10)
	s_nop 1
	v_mfma_f32_32x32x16_bf16 v[16:31], v[246:249], v[234:237], v[16:31]
	v_mfma_f32_32x32x16_bf16 v[0:15], v[58:61], v[234:237], v[0:15]
	global_load_dwordx4 v[234:237], v[66:67], off offset:32
	global_load_dwordx4 v[238:241], v[68:69], off offset:64
	global_load_dwordx4 v[242:245], v[68:69], off offset:80
	global_load_dwordx4 v[246:249], v[70:71], off offset:32
	global_load_dwordx4 v[58:61], v[72:73], off offset:32
	s_waitcnt vmcnt(12)
; DI unsigned cvtpk(float lo, float hi) { f32x2_t v = {lo, hi}; bf16x2_t b = __builtin_convertvector(v, bf16x2_t); return __builtin_bit_cast(unsigned, b); }
; DI void unpack8(const u32x4 w, float (&v)[8]) { v[0] = bflo(w.x); v[1] = bfhi(w.x); v[2] = bflo(w.y); v[3] = bfhi(w.y); v[4] = bflo(w.z); v[5] = bfhi(w.z); v[6] = bflo(w.w); v[7] = bfhi(w.w); }
; #define MFMA32(a, b, c) __builtin_amdgcn_mfma_f32_32x32x16_bf16((a), (b), (c), 0, 0, 0)
; DI void prep_compress_item(const Params& P, int l, int it, LAS unsigned char* lds, int wave, int lane) {
;     ...
;     for (int jj = 0; jj < 4; ++jj) {
;         const int j = 4 * wave + jj;
;         int tok = 16 * n + j; tok = tok > SEQ - 1 ? SEQ - 1 : tok;
;         const bf16_t* xp = hb + (size_t)(b * SEQ + tok) * NIN + col + 8 * h;
; #pragma unroll
;         for (int ds = 0; ds < 4; ++ds) {
;             float v[8]; unpack8(*(const u32x4*)(xp + 16 * ds), v);
;             const f32x4 p0 = *(const f32x4*)(pe + j * 64 + 16 * ds + 8 * h), p1 = *(const f32x4*)(pe + j * 64 + 16 * ds + 8 * h + 4);
;             u32x4 w; w.x = cvtpk(v[0] + p0[0], v[1] + p0[1]); w.y = cvtpk(v[2] + p0[2], v[3] + p0[3]); w.z = cvtpk(v[4] + p1[0], v[5] + p1[1]); w.w = cvtpk(v[6] + p1[2], v[7] + p1[3]);
;             const bf16x8 bfrag = __builtin_bit_cast(bf16x8, w);
;             const int k0 = j * 64 + 16 * ds + 8 * h;
;             const bf16x8 a0 = *(const bf16x8*)(cw + (size_t)r * 2048 + k0), a1 = *(const bf16x8*)(cw + (size_t)(32 + r) * 2048 + k0);
;             acc[0] = MFMA32(a0, bfrag, acc[0]); acc[1] = MFMA32(a1, bfrag, acc[1]);
	v_lshlrev_b32_e32 v62, 16, v132
	v_and_b32_e32 v63, 0xffff0000, v132
	v_lshlrev_b32_e32 v64, 16, v133
	v_and_b32_e32 v65, 0xffff0000, v133
	v_pk_add_f32 v[62:63], v[136:137], v[62:63]
	v_pk_add_f32 v[64:65], v[138:139], v[64:65]
	s_nop 0
	v_cvt_pk_bf16_f32 v132, v62, v63
	v_cvt_pk_bf16_f32 v133, v64, v65
	v_lshlrev_b32_e32 v62, 16, v134
	v_and_b32_e32 v63, 0xffff0000, v134
	v_lshlrev_b32_e32 v64, 16, v135
	v_and_b32_e32 v65, 0xffff0000, v135
	v_pk_add_f32 v[62:63], v[140:141], v[62:63]
	v_pk_add_f32 v[64:65], v[142:143], v[64:65]
	s_nop 0
	v_cvt_pk_bf16_f32 v134, v62, v63
	v_cvt_pk_bf16_f32 v135, v64, v65
	s_waitcnt vmcnt(10)
	s_nop 1
	v_mfma_f32_32x32x16_bf16 v[16:31], v[144:147], v[132:135], v[16:31]
	v_mfma_f32_32x32x16_bf16 v[0:15], v[148:151], v[132:135], v[0:15]
	global_load_dwordx4 v[132:135], v[66:67], off offset:64
	global_load_dwordx4 v[136:139], v[68:69], off offset:128
	global_load_dwordx4 v[140:143], v[68:69], off offset:144
	global_load_dwordx4 v[144:147], v[70:71], off offset:64
	global_load_dwordx4 v[148:151], v[72:73], off offset:64
	s_waitcnt vmcnt(12)
	v_lshlrev_b32_e32 v62, 16, v152
	v_and_b32_e32 v63, 0xffff0000, v152
	v_lshlrev_b32_e32 v64, 16, v153
	v_and_b32_e32 v65, 0xffff0000, v153
	v_pk_add_f32 v[62:63], v[156:157], v[62:63]
	v_pk_add_f32 v[64:65], v[158:159], v[64:65]
	s_nop 0
	v_cvt_pk_bf16_f32 v152, v62, v63
	v_cvt_pk_bf16_f32 v153, v64, v65
	v_lshlrev_b32_e32 v62, 16, v154
	v_and_b32_e32 v63, 0xffff0000, v154
	v_lshlrev_b32_e32 v64, 16, v155
	v_and_b32_e32 v65, 0xffff0000, v155
	v_pk_add_f32 v[62:63], v[220:221], v[62:63]
	v_pk_add_f32 v[64:65], v[222:223], v[64:65]
	s_nop 0
	v_cvt_pk_bf16_f32 v154, v62, v63
	v_cvt_pk_bf16_f32 v155, v64, v65
	s_waitcnt vmcnt(10)
	s_nop 1
	v_mfma_f32_32x32x16_bf16 v[16:31], v[226:229], v[152:155], v[16:31]
	v_mfma_f32_32x32x16_bf16 v[0:15], v[230:233], v[152:155], v[0:15]
	global_load_dwordx4 v[152:155], v[66:67], off offset:96
	global_load_dwordx4 v[156:159], v[68:69], off offset:192
	global_load_dwordx4 v[220:223], v[68:69], off offset:208
	global_load_dwordx4 v[226:229], v[70:71], off offset:96
	global_load_dwordx4 v[230:233], v[72:73], off offset:96
	s_waitcnt vmcnt(12)
	v_lshlrev_b32_e32 v62, 16, v234
	v_and_b32_e32 v63, 0xffff0000, v234
	v_lshlrev_b32_e32 v64, 16, v235
	v_and_b32_e32 v65, 0xffff0000, v235
	v_pk_add_f32 v[62:63], v[238:239], v[62:63]
	v_pk_add_f32 v[64:65], v[240:241], v[64:65]
	s_nop 0
	v_cvt_pk_bf16_f32 v234, v62, v63
	v_cvt_pk_bf16_f32 v235, v64, v65
	v_lshlrev_b32_e32 v62, 16, v236
	v_and_b32_e32 v63, 0xffff0000, v236
	v_lshlrev_b32_e32 v64, 16, v237
	v_and_b32_e32 v65, 0xffff0000, v237
	v_pk_add_f32 v[62:63], v[242:243], v[62:63]
	v_pk_add_f32 v[64:65], v[244:245], v[64:65]
	s_nop 0
	v_cvt_pk_bf16_f32 v236, v62, v63
	v_cvt_pk_bf16_f32 v237, v64, v65
	s_waitcnt vmcnt(10)
	s_nop 1
	v_mfma_f32_32x32x16_bf16 v[16:31], v[246:249], v[234:237], v[16:31]
	v_mfma_f32_32x32x16_bf16 v[0:15], v[58:61], v[234:237], v[0:15]
	v_add_u32_e32 v74, s52, v94
	v_min_i32_e32 v74, 0xfff, v74
	v_add_u32_e32 v74, s10, v74
	v_mad_i64_i32 v[66:67], s[58:59], v74, s82, v[54:55]
	v_lshl_add_u64 v[68:69], s[42:43], 2, v[56:57]
	v_lshl_add_u64 v[70:71], v[50:51], 0, v[44:45]
	v_lshl_add_u64 v[72:73], v[52:53], 0, v[44:45]
	global_load_dwordx4 v[234:237], v[66:67], off
	global_load_dwordx4 v[238:241], v[68:69], off
	global_load_dwordx4 v[242:245], v[68:69], off offset:16
	global_load_dwordx4 v[246:249], v[70:71], off
	global_load_dwordx4 v[58:61], v[72:73], off
	s_waitcnt vmcnt(12)
	v_lshlrev_b32_e32 v62, 16, v132
	v_and_b32_e32 v63, 0xffff0000, v132
	v_lshlrev_b32_e32 v64, 16, v133
	v_and_b32_e32 v65, 0xffff0000, v133
	v_pk_add_f32 v[62:63], v[136:137], v[62:63]
	v_pk_add_f32 v[64:65], v[138:139], v[64:65]
	s_nop 0
	v_cvt_pk_bf16_f32 v132, v62, v63
	v_cvt_pk_bf16_f32 v133, v64, v65
	v_lshlrev_b32_e32 v62, 16, v134
	v_and_b32_e32 v63, 0xffff0000, v134
	v_lshlrev_b32_e32 v64, 16, v135
	v_and_b32_e32 v65, 0xffff0000, v135
	v_pk_add_f32 v[62:63], v[140:141], v[62:63]
	v_pk_add_f32 v[64:65], v[142:143], v[64:65]
	s_nop 0
	v_cvt_pk_bf16_f32 v134, v62, v63
	v_cvt_pk_bf16_f32 v135, v64, v65
	s_waitcnt vmcnt(10)
	s_nop 1
	v_mfma_f32_32x32x16_bf16 v[16:31], v[144:147], v[132:135], v[16:31]
	v_mfma_f32_32x32x16_bf16 v[0:15], v[148:151], v[132:135], v[0:15]
	global_load_dwordx4 v[132:135], v[66:67], off offset:32
	global_load_dwordx4 v[136:139], v[68:69], off offset:64
	global_load_dwordx4 v[140:143], v[68:69], off offset:80
	global_load_dwordx4 v[144:147], v[70:71], off offset:32
	global_load_dwordx4 v[148:151], v[72:73], off offset:32
	s_waitcnt vmcnt(12)
	v_lshlrev_b32_e32 v62, 16, v152
	v_and_b32_e32 v63, 0xffff0000, v152
	v_lshlrev_b32_e32 v64, 16, v153
	v_and_b32_e32 v65, 0xffff0000, v153
	v_pk_add_f32 v[62:63], v[156:157], v[62:63]
	v_pk_add_f32 v[64:65], v[158:159], v[64:65]
	s_nop 0
	v_cvt_pk_bf16_f32 v152, v62, v63
	v_cvt_pk_bf16_f32 v153, v64, v65
	v_lshlrev_b32_e32 v62, 16, v154
	v_and_b32_e32 v63, 0xffff0000, v154
	v_lshlrev_b32_e32 v64, 16, v155
	v_and_b32_e32 v65, 0xffff0000, v155
	v_pk_add_f32 v[62:63], v[220:221], v[62:63]
	v_pk_add_f32 v[64:65], v[222:223], v[64:65]
	s_nop 0
	v_cvt_pk_bf16_f32 v154, v62, v63
	v_cvt_pk_bf16_f32 v155, v64, v65
	s_waitcnt vmcnt(10)
	s_nop 1
	v_mfma_f32_32x32x16_bf16 v[16:31], v[226:229], v[152:155], v[16:31]
	v_mfma_f32_32x32x16_bf16 v[0:15], v[230:233], v[152:155], v[0:15]
	global_load_dwordx4 v[152:155], v[66:67], off offset:64
	global_load_dwordx4 v[156:159], v[68:69], off offset:128
	global_load_dwordx4 v[220:223], v[68:69], off offset:144
	global_load_dwordx4 v[226:229], v[70:71], off offset:64
	global_load_dwordx4 v[230:233], v[72:73], off offset:64
	s_waitcnt vmcnt(12)
; DI unsigned cvtpk(float lo, float hi) { f32x2_t v = {lo, hi}; bf16x2_t b = __builtin_convertvector(v, bf16x2_t); return __builtin_bit_cast(unsigned, b); }
; DI void unpack8(const u32x4 w, float (&v)[8]) { v[0] = bflo(w.x); v[1] = bfhi(w.x); v[2] = bflo(w.y); v[3] = bfhi(w.y); v[4] = bflo(w.z); v[5] = bfhi(w.z); v[6] = bflo(w.w); v[7] = bfhi(w.w); }
; #define MFMA32(a, b, c) __builtin_amdgcn_mfma_f32_32x32x16_bf16((a), (b), (c), 0, 0, 0)
; DI void prep_compress_item(const Params& P, int l, int it, LAS unsigned char* lds, int wave, int lane) {
;     ...
;     for (int jj = 0; jj < 4; ++jj) {
;         const int j = 4 * wave + jj;
;         int tok = 16 * n + j; tok = tok > SEQ - 1 ? SEQ - 1 : tok;
;         const bf16_t* xp = hb + (size_t)(b * SEQ + tok) * NIN + col + 8 * h;
; #pragma unroll
;         for (int ds = 0; ds < 4; ++ds) {
;             float v[8]; unpack8(*(const u32x4*)(xp + 16 * ds), v);
;             const f32x4 p0 = *(const f32x4*)(pe + j * 64 + 16 * ds + 8 * h), p1 = *(const f32x4*)(pe + j * 64 + 16 * ds + 8 * h + 4);
;             u32x4 w; w.x = cvtpk(v[0] + p0[0], v[1] + p0[1]); w.y = cvtpk(v[2] + p0[2], v[3] + p0[3]); w.z = cvtpk(v[4] + p1[0], v[5] + p1[1]); w.w = cvtpk(v[6] + p1[2], v[7] + p1[3]);
;             const bf16x8 bfrag = __builtin_bit_cast(bf16x8, w);
;             const int k0 = j * 64 + 16 * ds + 8 * h;
;             const bf16x8 a0 = *(const bf16x8*)(cw + (size_t)r * 2048 + k0), a1 = *(const bf16x8*)(cw + (size_t)(32 + r) * 2048 + k0);
;             acc[0] = MFMA32(a0, bfrag, acc[0]); acc[1] = MFMA32(a1, bfrag, acc[1]);
	v_lshlrev_b32_e32 v62, 16, v234
	v_and_b32_e32 v63, 0xffff0000, v234
	v_lshlrev_b32_e32 v64, 16, v235
	v_and_b32_e32 v65, 0xffff0000, v235
	v_pk_add_f32 v[62:63], v[238:239], v[62:63]
	v_pk_add_f32 v[64:65], v[240:241], v[64:65]
	s_nop 0
	v_cvt_pk_bf16_f32 v234, v62, v63
	v_cvt_pk_bf16_f32 v235, v64, v65
	v_lshlrev_b32_e32 v62, 16, v236
	v_and_b32_e32 v63, 0xffff0000, v236
	v_lshlrev_b32_e32 v64, 16, v237
	v_and_b32_e32 v65, 0xffff0000, v237
	v_pk_add_f32 v[62:63], v[242:243], v[62:63]
	v_pk_add_f32 v[64:65], v[244:245], v[64:65]
	s_nop 0
	v_cvt_pk_bf16_f32 v236, v62, v63
	v_cvt_pk_bf16_f32 v237, v64, v65
	s_waitcnt vmcnt(10)
	s_nop 1
	v_mfma_f32_32x32x16_bf16 v[16:31], v[246:249], v[234:237], v[16:31]
	v_mfma_f32_32x32x16_bf16 v[0:15], v[58:61], v[234:237], v[0:15]
	global_load_dwordx4 v[234:237], v[66:67], off offset:96
	global_load_dwordx4 v[238:241], v[68:69], off offset:192
	global_load_dwordx4 v[242:245], v[68:69], off offset:208
	global_load_dwordx4 v[246:249], v[70:71], off offset:96
	global_load_dwordx4 v[58:61], v[72:73], off offset:96
	s_waitcnt vmcnt(12)
	v_lshlrev_b32_e32 v62, 16, v132
	v_and_b32_e32 v63, 0xffff0000, v132
	v_lshlrev_b32_e32 v64, 16, v133
	v_and_b32_e32 v65, 0xffff0000, v133
	v_pk_add_f32 v[62:63], v[136:137], v[62:63]
	v_pk_add_f32 v[64:65], v[138:139], v[64:65]
	s_nop 0
	v_cvt_pk_bf16_f32 v132, v62, v63
	v_cvt_pk_bf16_f32 v133, v64, v65
	v_lshlrev_b32_e32 v62, 16, v134
	v_and_b32_e32 v63, 0xffff0000, v134
	v_lshlrev_b32_e32 v64, 16, v135
	v_and_b32_e32 v65, 0xffff0000, v135
	v_pk_add_f32 v[62:63], v[140:141], v[62:63]
	v_pk_add_f32 v[64:65], v[142:143], v[64:65]
	s_nop 0
	v_cvt_pk_bf16_f32 v134, v62, v63
	v_cvt_pk_bf16_f32 v135, v64, v65
	s_waitcnt vmcnt(10)
	s_nop 1
	v_mfma_f32_32x32x16_bf16 v[16:31], v[144:147], v[132:135], v[16:31]
	v_mfma_f32_32x32x16_bf16 v[0:15], v[148:151], v[132:135], v[0:15]
	v_add_u32_e32 v74, s53, v94
	v_min_i32_e32 v74, 0xfff, v74
	v_add_u32_e32 v74, s10, v74
	v_mad_i64_i32 v[66:67], s[58:59], v74, s82, v[54:55]
	v_lshl_add_u64 v[68:69], s[48:49], 2, v[56:57]
	v_lshl_add_u64 v[70:71], v[50:51], 0, v[46:47]
	v_lshl_add_u64 v[72:73], v[52:53], 0, v[46:47]
	global_load_dwordx4 v[132:135], v[66:67], off
	global_load_dwordx4 v[136:139], v[68:69], off
	global_load_dwordx4 v[140:143], v[68:69], off offset:16
	global_load_dwordx4 v[144:147], v[70:71], off
	global_load_dwordx4 v[148:151], v[72:73], off
	s_waitcnt vmcnt(12)
	v_lshlrev_b32_e32 v62, 16, v152
	v_and_b32_e32 v63, 0xffff0000, v152
	v_lshlrev_b32_e32 v64, 16, v153
	v_and_b32_e32 v65, 0xffff0000, v153
	v_pk_add_f32 v[62:63], v[156:157], v[62:63]
	v_pk_add_f32 v[64:65], v[158:159], v[64:65]
	s_nop 0
	v_cvt_pk_bf16_f32 v152, v62, v63
	v_cvt_pk_bf16_f32 v153, v64, v65
	v_lshlrev_b32_e32 v62, 16, v154
	v_and_b32_e32 v63, 0xffff0000, v154
	v_lshlrev_b32_e32 v64, 16, v155
	v_and_b32_e32 v65, 0xffff0000, v155
	v_pk_add_f32 v[62:63], v[220:221], v[62:63]
	v_pk_add_f32 v[64:65], v[222:223], v[64:65]
	s_nop 0
	v_cvt_pk_bf16_f32 v154, v62, v63
	v_cvt_pk_bf16_f32 v155, v64, v65
	s_waitcnt vmcnt(10)
	s_nop 1
	v_mfma_f32_32x32x16_bf16 v[16:31], v[226:229], v[152:155], v[16:31]
	v_mfma_f32_32x32x16_bf16 v[0:15], v[230:233], v[152:155], v[0:15]
	global_load_dwordx4 v[152:155], v[66:67], off offset:32
	global_load_dwordx4 v[156:159], v[68:69], off offset:64
	global_load_dwordx4 v[220:223], v[68:69], off offset:80
	global_load_dwordx4 v[226:229], v[70:71], off offset:32
	global_load_dwordx4 v[230:233], v[72:73], off offset:32
	s_waitcnt vmcnt(12)
	v_lshlrev_b32_e32 v62, 16, v234
	v_and_b32_e32 v63, 0xffff0000, v234
	v_lshlrev_b32_e32 v64, 16, v235
	v_and_b32_e32 v65, 0xffff0000, v235
	v_pk_add_f32 v[62:63], v[238:239], v[62:63]
	v_pk_add_f32 v[64:65], v[240:241], v[64:65]
	s_nop 0
	v_cvt_pk_bf16_f32 v234, v62, v63
	v_cvt_pk_bf16_f32 v235, v64, v65
	v_lshlrev_b32_e32 v62, 16, v236
	v_and_b32_e32 v63, 0xffff0000, v236
	v_lshlrev_b32_e32 v64, 16, v237
	v_and_b32_e32 v65, 0xffff0000, v237
	v_pk_add_f32 v[62:63], v[242:243], v[62:63]
	v_pk_add_f32 v[64:65], v[244:245], v[64:65]
	s_nop 0
	v_cvt_pk_bf16_f32 v236, v62, v63
	v_cvt_pk_bf16_f32 v237, v64, v65
	s_waitcnt vmcnt(10)
	s_nop 1
	v_mfma_f32_32x32x16_bf16 v[16:31], v[246:249], v[234:237], v[16:31]
	v_mfma_f32_32x32x16_bf16 v[0:15], v[58:61], v[234:237], v[0:15]
	global_load_dwordx4 v[234:237], v[66:67], off offset:64
	global_load_dwordx4 v[238:241], v[68:69], off offset:128
	global_load_dwordx4 v[242:245], v[68:69], off offset:144
	global_load_dwordx4 v[246:249], v[70:71], off offset:64
	global_load_dwordx4 v[58:61], v[72:73], off offset:64
	s_waitcnt vmcnt(12)
	v_lshlrev_b32_e32 v62, 16, v132
	v_and_b32_e32 v63, 0xffff0000, v132
	v_lshlrev_b32_e32 v64, 16, v133
	v_and_b32_e32 v65, 0xffff0000, v133
	v_pk_add_f32 v[62:63], v[136:137], v[62:63]
	v_pk_add_f32 v[64:65], v[138:139], v[64:65]
	s_nop 0
	v_cvt_pk_bf16_f32 v132, v62, v63
	v_cvt_pk_bf16_f32 v133, v64, v65
	v_lshlrev_b32_e32 v62, 16, v134
	v_and_b32_e32 v63, 0xffff0000, v134
	v_lshlrev_b32_e32 v64, 16, v135
	v_and_b32_e32 v65, 0xffff0000, v135
	v_pk_add_f32 v[62:63], v[140:141], v[62:63]
	v_pk_add_f32 v[64:65], v[142:143], v[64:65]
	s_nop 0
	v_cvt_pk_bf16_f32 v134, v62, v63
	v_cvt_pk_bf16_f32 v135, v64, v65
	s_waitcnt vmcnt(10)
	s_nop 1
	v_mfma_f32_32x32x16_bf16 v[16:31], v[144:147], v[132:135], v[16:31]
	v_mfma_f32_32x32x16_bf16 v[0:15], v[148:151], v[132:135], v[0:15]
	global_load_dwordx4 v[132:135], v[66:67], off offset:96
	global_load_dwordx4 v[136:139], v[68:69], off offset:192
	global_load_dwordx4 v[140:143], v[68:69], off offset:208
	global_load_dwordx4 v[144:147], v[70:71], off offset:96
	global_load_dwordx4 v[148:151], v[72:73], off offset:96
	s_waitcnt vmcnt(12)
; #define LAS __attribute__((address_space(3)))
; DI unsigned cvtpk(float lo, float hi) { f32x2_t v = {lo, hi}; bf16x2_t b = __builtin_convertvector(v, bf16x2_t); return __builtin_bit_cast(unsigned, b); }
; DI void unpack8(const u32x4 w, float (&v)[8]) { v[0] = bflo(w.x); v[1] = bfhi(w.x); v[2] = bflo(w.y); v[3] = bfhi(w.y); v[4] = bflo(w.z); v[5] = bfhi(w.z); v[6] = bflo(w.w); v[7] = bfhi(w.w); }
; #define MFMA32(a, b, c) __builtin_amdgcn_mfma_f32_32x32x16_bf16((a), (b), (c), 0, 0, 0)
; DI void prep_compress_item(const Params& P, int l, int it, LAS unsigned char* lds, int wave, int lane) {
;     ...
;         for (int ds = 0; ds < 4; ++ds) {
;             float v[8]; unpack8(*(const u32x4*)(xp + 16 * ds), v);
;             const f32x4 p0 = *(const f32x4*)(pe + j * 64 + 16 * ds + 8 * h), p1 = *(const f32x4*)(pe + j * 64 + 16 * ds + 8 * h + 4);
;             u32x4 w; w.x = cvtpk(v[0] + p0[0], v[1] + p0[1]); w.y = cvtpk(v[2] + p0[2], v[3] + p0[3]); w.z = cvtpk(v[4] + p1[0], v[5] + p1[1]); w.w = cvtpk(v[6] + p1[2], v[7] + p1[3]);
;             const bf16x8 bfrag = __builtin_bit_cast(bf16x8, w);
;             const int k0 = j * 64 + 16 * ds + 8 * h;
;             const bf16x8 a0 = *(const bf16x8*)(cw + (size_t)r * 2048 + k0), a1 = *(const bf16x8*)(cw + (size_t)(32 + r) * 2048 + k0);
;             acc[0] = MFMA32(a0, bfrag, acc[0]); acc[1] = MFMA32(a1, bfrag, acc[1]);
;         }
;     }
;     LAS float* part = (LAS float*)lds;
; #pragma unroll
;     for (int et = 0; et < 2; ++et)
; #pragma unroll
;         for (int i = 0; i < 16; ++i) part[(wave * 32 + et * 16 + i) * 64 + lane] = acc[et][i];
;     __syncthreads();
;     if (wave == 0) {
; #pragma unroll
;         for (int et = 0; et < 2; ++et)
; #pragma unroll
;             for (int i = 0; i < 16; ++i) { float a = acc[et][i];
; #pragma unroll
;                 for (int w = 1; w < 8; ++w) a += part[(w * 32 + et * 16 + i) * 64 + lane];
	v_lshlrev_b32_e32 v62, 16, v152
	v_and_b32_e32 v63, 0xffff0000, v152
	v_lshlrev_b32_e32 v64, 16, v153
	v_and_b32_e32 v65, 0xffff0000, v153
	v_pk_add_f32 v[62:63], v[156:157], v[62:63]
	v_pk_add_f32 v[64:65], v[158:159], v[64:65]
	s_nop 0
	v_cvt_pk_bf16_f32 v152, v62, v63
	v_cvt_pk_bf16_f32 v153, v64, v65
	v_lshlrev_b32_e32 v62, 16, v154
	v_and_b32_e32 v63, 0xffff0000, v154
	v_lshlrev_b32_e32 v64, 16, v155
	v_and_b32_e32 v65, 0xffff0000, v155
	v_pk_add_f32 v[62:63], v[220:221], v[62:63]
	v_pk_add_f32 v[64:65], v[222:223], v[64:65]
	s_nop 0
	v_cvt_pk_bf16_f32 v154, v62, v63
	v_cvt_pk_bf16_f32 v155, v64, v65
	s_waitcnt vmcnt(10)
	s_nop 1
	v_mfma_f32_32x32x16_bf16 v[16:31], v[226:229], v[152:155], v[16:31]
	v_mfma_f32_32x32x16_bf16 v[0:15], v[230:233], v[152:155], v[0:15]
	s_waitcnt vmcnt(7)
	v_lshlrev_b32_e32 v62, 16, v234
	v_and_b32_e32 v63, 0xffff0000, v234
	v_lshlrev_b32_e32 v64, 16, v235
	v_and_b32_e32 v65, 0xffff0000, v235
	v_pk_add_f32 v[62:63], v[238:239], v[62:63]
	v_pk_add_f32 v[64:65], v[240:241], v[64:65]
	s_nop 0
	v_cvt_pk_bf16_f32 v234, v62, v63
	v_cvt_pk_bf16_f32 v235, v64, v65
	v_lshlrev_b32_e32 v62, 16, v236
	v_and_b32_e32 v63, 0xffff0000, v236
	v_lshlrev_b32_e32 v64, 16, v237
	v_and_b32_e32 v65, 0xffff0000, v237
	v_pk_add_f32 v[62:63], v[242:243], v[62:63]
	v_pk_add_f32 v[64:65], v[244:245], v[64:65]
	s_nop 0
	v_cvt_pk_bf16_f32 v236, v62, v63
	v_cvt_pk_bf16_f32 v237, v64, v65
	s_waitcnt vmcnt(5)
	s_nop 1
	v_mfma_f32_32x32x16_bf16 v[16:31], v[246:249], v[234:237], v[16:31]
	v_mfma_f32_32x32x16_bf16 v[0:15], v[58:61], v[234:237], v[0:15]
	s_waitcnt vmcnt(2)
	v_lshlrev_b32_e32 v62, 16, v132
	v_and_b32_e32 v63, 0xffff0000, v132
	v_lshlrev_b32_e32 v64, 16, v133
	v_and_b32_e32 v65, 0xffff0000, v133
	v_pk_add_f32 v[62:63], v[136:137], v[62:63]
	v_pk_add_f32 v[64:65], v[138:139], v[64:65]
	s_nop 0
	v_cvt_pk_bf16_f32 v132, v62, v63
	v_cvt_pk_bf16_f32 v133, v64, v65
	v_lshlrev_b32_e32 v62, 16, v134
	v_and_b32_e32 v63, 0xffff0000, v134
	v_lshlrev_b32_e32 v64, 16, v135
	v_and_b32_e32 v65, 0xffff0000, v135
	v_pk_add_f32 v[62:63], v[140:141], v[62:63]
	v_pk_add_f32 v[64:65], v[142:143], v[64:65]
	s_nop 0
	v_cvt_pk_bf16_f32 v134, v62, v63
	v_cvt_pk_bf16_f32 v135, v64, v65
	s_waitcnt vmcnt(0)
	s_nop 1
	v_mfma_f32_32x32x16_bf16 v[16:31], v[144:147], v[132:135], v[16:31]
	v_mfma_f32_32x32x16_bf16 v[0:15], v[148:151], v[132:135], v[0:15]
	v_add_u32_e32 v39, s54, v89
	s_nop 3
	s_nop 9
	ds_write2st64_b32 v39, v16, v17 offset1:1
	ds_write2st64_b32 v39, v18, v19 offset0:2 offset1:3
	ds_write2st64_b32 v39, v20, v21 offset0:4 offset1:5
	ds_write2st64_b32 v39, v22, v23 offset0:6 offset1:7
	ds_write2st64_b32 v39, v24, v25 offset0:8 offset1:9
	ds_write2st64_b32 v39, v26, v27 offset0:10 offset1:11
	ds_write2st64_b32 v39, v28, v29 offset0:12 offset1:13
	ds_write2st64_b32 v39, v30, v31 offset0:14 offset1:15
	ds_write2st64_b32 v39, v0, v1 offset0:16 offset1:17
	ds_write2st64_b32 v39, v2, v3 offset0:18 offset1:19
	ds_write2st64_b32 v39, v4, v5 offset0:20 offset1:21
	ds_write2st64_b32 v39, v6, v7 offset0:22 offset1:23
	ds_write2st64_b32 v39, v8, v9 offset0:24 offset1:25
	ds_write2st64_b32 v39, v10, v11 offset0:26 offset1:27
	ds_write2st64_b32 v39, v12, v13 offset0:28 offset1:29
	ds_write2st64_b32 v39, v14, v15 offset0:30 offset1:31
	s_waitcnt lgkmcnt(0)
	s_barrier
	s_cbranch_vccnz .LBB0_329
	ds_read2st64_b32 v[50:51], v89 offset0:32 offset1:33
	ds_read2st64_b32 v[66:67], v89 offset0:64 offset1:65
	ds_read2st64_b32 v[68:69], v89 offset0:96 offset1:97
	ds_read2st64_b32 v[70:71], v89 offset0:128 offset1:129
	ds_read2st64_b32 v[72:73], v89 offset0:160 offset1:161
	ds_read2st64_b32 v[74:75], v89 offset0:192 offset1:193
	ds_read2st64_b32 v[76:77], v89 offset0:224 offset1:225
	ds_read2st64_b32 v[64:65], v89 offset0:34 offset1:35
	ds_read2st64_b32 v[62:63], v89 offset0:66 offset1:67
	ds_read2st64_b32 v[60:61], v89 offset0:98 offset1:99
	ds_read2st64_b32 v[58:59], v89 offset0:130 offset1:131
	ds_read2st64_b32 v[56:57], v89 offset0:162 offset1:163
	ds_read2st64_b32 v[54:55], v89 offset0:194 offset1:195
	ds_read2st64_b32 v[52:53], v89 offset0:226 offset1:227
	ds_read2st64_b32 v[78:79], v89 offset0:36 offset1:37
	ds_read2st64_b32 v[80:81], v89 offset0:68 offset1:69
	ds_read2st64_b32 v[82:83], v89 offset0:100 offset1:101
	ds_read2st64_b32 v[84:85], v89 offset0:132 offset1:133
	ds_read2st64_b32 v[96:97], v89 offset0:164 offset1:165
	ds_read2st64_b32 v[98:99], v89 offset0:196 offset1:197
	ds_read2st64_b32 v[100:101], v89 offset0:228 offset1:229
	s_waitcnt lgkmcnt(14)
	v_pk_add_f32 v[16:17], v[16:17], v[50:51]
	s_andn2_b64 vcc, exec, s[0:1]
	v_pk_add_f32 v[16:17], v[16:17], v[66:67]
	s_nop 0
	v_pk_add_f32 v[16:17], v[16:17], v[68:69]
	s_nop 0
	v_pk_add_f32 v[16:17], v[16:17], v[70:71]
	s_nop 0
	v_pk_add_f32 v[16:17], v[16:17], v[72:73]
	s_nop 0
	v_pk_add_f32 v[16:17], v[16:17], v[74:75]
	s_nop 0
	v_pk_add_f32 v[50:51], v[16:17], v[76:77]
	s_waitcnt lgkmcnt(6)
	v_pk_add_f32 v[16:17], v[20:21], v[78:79]
	ds_read2st64_b32 v[66:67], v89 offset0:38 offset1:39
	ds_read2st64_b32 v[68:69], v89 offset0:70 offset1:71
	ds_read2st64_b32 v[70:71], v89 offset0:102 offset1:103
	ds_read2st64_b32 v[72:73], v89 offset0:134 offset1:135
	ds_read2st64_b32 v[74:75], v89 offset0:166 offset1:167
	ds_read2st64_b32 v[76:77], v89 offset0:198 offset1:199
	ds_read2st64_b32 v[78:79], v89 offset0:230 offset1:231
	s_waitcnt lgkmcnt(12)
	v_pk_add_f32 v[16:17], v[16:17], v[80:81]
	s_waitcnt lgkmcnt(11)
	v_pk_add_f32 v[16:17], v[16:17], v[82:83]
	s_waitcnt lgkmcnt(10)
	v_pk_add_f32 v[16:17], v[16:17], v[84:85]
	s_waitcnt lgkmcnt(9)
	v_pk_add_f32 v[16:17], v[16:17], v[96:97]
	s_waitcnt lgkmcnt(8)
; DI void prep_compress_item(const Params& P, int l, int it, LAS unsigned char* lds, int wave, int lane) {
;     ...
;     if (wave == 0) {
; #pragma unroll
;         for (int et = 0; et < 2; ++et)
; #pragma unroll
;             for (int i = 0; i < 16; ++i) { float a = acc[et][i];
; #pragma unroll
;                 for (int w = 1; w < 8; ++w) a += part[(w * 32 + et * 16 + i) * 64 + lane];
;                 acc[et][i] = a; }
	v_pk_add_f32 v[16:17], v[16:17], v[98:99]
	s_waitcnt lgkmcnt(7)
	v_pk_add_f32 v[20:21], v[16:17], v[100:101]
	v_pk_add_f32 v[16:17], v[18:19], v[64:65]
	s_waitcnt lgkmcnt(6)
	v_pk_add_f32 v[18:19], v[22:23], v[66:67]
	v_pk_add_f32 v[16:17], v[16:17], v[62:63]
	s_waitcnt lgkmcnt(5)
	v_pk_add_f32 v[18:19], v[18:19], v[68:69]
	v_pk_add_f32 v[16:17], v[16:17], v[60:61]
	s_waitcnt lgkmcnt(4)
	v_pk_add_f32 v[18:19], v[18:19], v[70:71]
	v_pk_add_f32 v[16:17], v[16:17], v[58:59]
	s_waitcnt lgkmcnt(3)
	v_pk_add_f32 v[18:19], v[18:19], v[72:73]
	v_pk_add_f32 v[16:17], v[16:17], v[56:57]
	s_waitcnt lgkmcnt(2)
	v_pk_add_f32 v[18:19], v[18:19], v[74:75]
	v_pk_add_f32 v[16:17], v[16:17], v[54:55]
	s_waitcnt lgkmcnt(1)
	v_pk_add_f32 v[18:19], v[18:19], v[76:77]
	v_pk_add_f32 v[16:17], v[16:17], v[52:53]
	ds_read2st64_b32 v[22:23], v89 offset0:40 offset1:41
	ds_read2st64_b32 v[52:53], v89 offset0:72 offset1:73
	ds_read2st64_b32 v[54:55], v89 offset0:104 offset1:105
	ds_read2st64_b32 v[56:57], v89 offset0:136 offset1:137
	ds_read2st64_b32 v[58:59], v89 offset0:168 offset1:169
	ds_read2st64_b32 v[60:61], v89 offset0:200 offset1:201
	ds_read2st64_b32 v[62:63], v89 offset0:232 offset1:233
	s_waitcnt lgkmcnt(6)
	v_pk_add_f32 v[22:23], v[24:25], v[22:23]
	v_pk_add_f32 v[18:19], v[18:19], v[78:79]
	s_waitcnt lgkmcnt(5)
	v_pk_add_f32 v[22:23], v[22:23], v[52:53]
	s_waitcnt lgkmcnt(4)
	v_pk_add_f32 v[22:23], v[22:23], v[54:55]
	s_waitcnt lgkmcnt(3)
	v_pk_add_f32 v[22:23], v[22:23], v[56:57]
	s_waitcnt lgkmcnt(2)
	v_pk_add_f32 v[22:23], v[22:23], v[58:59]
	s_waitcnt lgkmcnt(1)
	v_pk_add_f32 v[22:23], v[22:23], v[60:61]
	s_waitcnt lgkmcnt(0)
	v_pk_add_f32 v[24:25], v[22:23], v[62:63]
	ds_read2st64_b32 v[22:23], v89 offset0:42 offset1:43
	ds_read2st64_b32 v[52:53], v89 offset0:74 offset1:75
	ds_read2st64_b32 v[54:55], v89 offset0:106 offset1:107
	ds_read2st64_b32 v[56:57], v89 offset0:138 offset1:139
	ds_read2st64_b32 v[58:59], v89 offset0:170 offset1:171
	ds_read2st64_b32 v[60:61], v89 offset0:202 offset1:203
	ds_read2st64_b32 v[62:63], v89 offset0:234 offset1:235
	s_waitcnt lgkmcnt(6)
	v_pk_add_f32 v[22:23], v[26:27], v[22:23]
	s_waitcnt lgkmcnt(5)
	v_pk_add_f32 v[22:23], v[22:23], v[52:53]
	s_waitcnt lgkmcnt(4)
	v_pk_add_f32 v[22:23], v[22:23], v[54:55]
	s_waitcnt lgkmcnt(3)
	v_pk_add_f32 v[22:23], v[22:23], v[56:57]
	s_waitcnt lgkmcnt(2)
	v_pk_add_f32 v[22:23], v[22:23], v[58:59]
	s_waitcnt lgkmcnt(1)
	v_pk_add_f32 v[22:23], v[22:23], v[60:61]
	s_waitcnt lgkmcnt(0)
	v_pk_add_f32 v[22:23], v[22:23], v[62:63]
	ds_read2st64_b32 v[84:85], v89 offset0:44 offset1:45
	ds_read2st64_b32 v[82:83], v89 offset0:76 offset1:77
	ds_read2st64_b32 v[80:81], v89 offset0:108 offset1:109
	ds_read2st64_b32 v[78:79], v89 offset0:140 offset1:141
	ds_read2st64_b32 v[76:77], v89 offset0:172 offset1:173
	ds_read2st64_b32 v[74:75], v89 offset0:204 offset1:205
	ds_read2st64_b32 v[72:73], v89 offset0:236 offset1:237
	ds_read2st64_b32 v[58:59], v89 offset0:46 offset1:47
	ds_read2st64_b32 v[60:61], v89 offset0:78 offset1:79
	ds_read2st64_b32 v[62:63], v89 offset0:110 offset1:111
	ds_read2st64_b32 v[64:65], v89 offset0:142 offset1:143
	ds_read2st64_b32 v[66:67], v89 offset0:174 offset1:175
	ds_read2st64_b32 v[68:69], v89 offset0:206 offset1:207
	ds_read2st64_b32 v[70:71], v89 offset0:238 offset1:239
	ds_read2st64_b32 v[26:27], v89 offset0:48 offset1:49
	ds_read2st64_b32 v[52:53], v89 offset0:80 offset1:81
	ds_read2st64_b32 v[54:55], v89 offset0:112 offset1:113
	ds_read2st64_b32 v[56:57], v89 offset0:144 offset1:145
	ds_read2st64_b32 v[96:97], v89 offset0:176 offset1:177
	ds_read2st64_b32 v[98:99], v89 offset0:208 offset1:209
	ds_read2st64_b32 v[100:101], v89 offset0:240 offset1:241
	s_waitcnt lgkmcnt(6)
	v_pk_add_f32 v[0:1], v[0:1], v[26:27]
	v_pk_add_f32 v[28:29], v[28:29], v[84:85]
	s_waitcnt lgkmcnt(5)
	v_pk_add_f32 v[0:1], v[0:1], v[52:53]
	v_pk_add_f32 v[28:29], v[28:29], v[82:83]
	s_waitcnt lgkmcnt(4)
	v_pk_add_f32 v[0:1], v[0:1], v[54:55]
	v_pk_add_f32 v[28:29], v[28:29], v[80:81]
	s_waitcnt lgkmcnt(3)
	v_pk_add_f32 v[0:1], v[0:1], v[56:57]
	v_pk_add_f32 v[28:29], v[28:29], v[78:79]
	s_waitcnt lgkmcnt(2)
	v_pk_add_f32 v[0:1], v[0:1], v[96:97]
	v_pk_add_f32 v[28:29], v[28:29], v[76:77]
	s_waitcnt lgkmcnt(1)
	v_pk_add_f32 v[0:1], v[0:1], v[98:99]
	v_pk_add_f32 v[28:29], v[28:29], v[74:75]
	s_waitcnt lgkmcnt(0)
	v_pk_add_f32 v[26:27], v[0:1], v[100:101]
	ds_read2st64_b32 v[0:1], v89 offset0:50 offset1:51
	ds_read2st64_b32 v[52:53], v89 offset0:82 offset1:83
	ds_read2st64_b32 v[54:55], v89 offset0:114 offset1:115
	ds_read2st64_b32 v[56:57], v89 offset0:146 offset1:147
	ds_read2st64_b32 v[96:97], v89 offset0:178 offset1:179
	ds_read2st64_b32 v[98:99], v89 offset0:210 offset1:211
	ds_read2st64_b32 v[100:101], v89 offset0:242 offset1:243
	s_waitcnt lgkmcnt(6)
	v_pk_add_f32 v[0:1], v[2:3], v[0:1]
	v_pk_add_f32 v[28:29], v[28:29], v[72:73]
	s_waitcnt lgkmcnt(5)
	v_pk_add_f32 v[0:1], v[0:1], v[52:53]
	v_pk_add_f32 v[30:31], v[30:31], v[58:59]
	s_waitcnt lgkmcnt(4)
	v_pk_add_f32 v[0:1], v[0:1], v[54:55]
	v_pk_add_f32 v[30:31], v[30:31], v[60:61]
	s_waitcnt lgkmcnt(3)
	v_pk_add_f32 v[0:1], v[0:1], v[56:57]
	v_pk_add_f32 v[30:31], v[30:31], v[62:63]
	s_waitcnt lgkmcnt(2)
; DI void prep_compress_item(const Params& P, int l, int it, LAS unsigned char* lds, int wave, int lane) {
;     ...
;     if (wave == 0) {
; #pragma unroll
;         for (int et = 0; et < 2; ++et)
; #pragma unroll
;             for (int i = 0; i < 16; ++i) { float a = acc[et][i];
; #pragma unroll
;                 for (int w = 1; w < 8; ++w) a += part[(w * 32 + et * 16 + i) * 64 + lane];
;                 acc[et][i] = a; }
	v_pk_add_f32 v[0:1], v[0:1], v[96:97]
	v_pk_add_f32 v[30:31], v[30:31], v[64:65]
	s_waitcnt lgkmcnt(1)
	v_pk_add_f32 v[0:1], v[0:1], v[98:99]
	v_pk_add_f32 v[30:31], v[30:31], v[66:67]
	s_waitcnt lgkmcnt(0)
	v_pk_add_f32 v[52:53], v[0:1], v[100:101]
	ds_read2st64_b32 v[0:1], v89 offset0:52 offset1:53
	ds_read2st64_b32 v[2:3], v89 offset0:84 offset1:85
	ds_read2st64_b32 v[54:55], v89 offset0:116 offset1:117
	ds_read2st64_b32 v[56:57], v89 offset0:148 offset1:149
	ds_read2st64_b32 v[96:97], v89 offset0:180 offset1:181
	ds_read2st64_b32 v[98:99], v89 offset0:212 offset1:213
	ds_read2st64_b32 v[100:101], v89 offset0:244 offset1:245
	s_waitcnt lgkmcnt(6)
	v_pk_add_f32 v[0:1], v[4:5], v[0:1]
	v_pk_add_f32 v[30:31], v[30:31], v[68:69]
	s_waitcnt lgkmcnt(5)
	v_pk_add_f32 v[0:1], v[0:1], v[2:3]
	v_pk_add_f32 v[30:31], v[30:31], v[70:71]
	s_waitcnt lgkmcnt(4)
	v_pk_add_f32 v[0:1], v[0:1], v[54:55]
	s_waitcnt lgkmcnt(3)
	v_pk_add_f32 v[0:1], v[0:1], v[56:57]
	s_waitcnt lgkmcnt(2)
	v_pk_add_f32 v[0:1], v[0:1], v[96:97]
	s_waitcnt lgkmcnt(1)
	v_pk_add_f32 v[0:1], v[0:1], v[98:99]
	s_waitcnt lgkmcnt(0)
	v_pk_add_f32 v[54:55], v[0:1], v[100:101]
	ds_read2st64_b32 v[0:1], v89 offset0:54 offset1:55
	ds_read2st64_b32 v[2:3], v89 offset0:86 offset1:87
	ds_read2st64_b32 v[4:5], v89 offset0:118 offset1:119
	ds_read2st64_b32 v[56:57], v89 offset0:150 offset1:151
	ds_read2st64_b32 v[96:97], v89 offset0:182 offset1:183
	ds_read2st64_b32 v[98:99], v89 offset0:214 offset1:215
	ds_read2st64_b32 v[100:101], v89 offset0:246 offset1:247
	s_waitcnt lgkmcnt(6)
	v_pk_add_f32 v[0:1], v[6:7], v[0:1]
	s_waitcnt lgkmcnt(5)
	v_pk_add_f32 v[0:1], v[0:1], v[2:3]
	s_waitcnt lgkmcnt(4)
	v_pk_add_f32 v[0:1], v[0:1], v[4:5]
	s_waitcnt lgkmcnt(3)
	v_pk_add_f32 v[0:1], v[0:1], v[56:57]
	s_waitcnt lgkmcnt(2)
	v_pk_add_f32 v[0:1], v[0:1], v[96:97]
	s_waitcnt lgkmcnt(1)
	v_pk_add_f32 v[0:1], v[0:1], v[98:99]
	s_waitcnt lgkmcnt(0)
	v_pk_add_f32 v[56:57], v[0:1], v[100:101]
	ds_read2st64_b32 v[0:1], v89 offset0:56 offset1:57
	ds_read2st64_b32 v[2:3], v89 offset0:88 offset1:89
	ds_read2st64_b32 v[4:5], v89 offset0:120 offset1:121
	ds_read2st64_b32 v[6:7], v89 offset0:152 offset1:153
	ds_read2st64_b32 v[96:97], v89 offset0:184 offset1:185
	ds_read2st64_b32 v[98:99], v89 offset0:216 offset1:217
	ds_read2st64_b32 v[100:101], v89 offset0:248 offset1:249
	s_waitcnt lgkmcnt(6)
	v_pk_add_f32 v[0:1], v[8:9], v[0:1]
	s_waitcnt lgkmcnt(5)
	v_pk_add_f32 v[0:1], v[0:1], v[2:3]
	s_waitcnt lgkmcnt(4)
	v_pk_add_f32 v[0:1], v[0:1], v[4:5]
	s_waitcnt lgkmcnt(3)
	v_pk_add_f32 v[0:1], v[0:1], v[6:7]
	s_waitcnt lgkmcnt(2)
	v_pk_add_f32 v[0:1], v[0:1], v[96:97]
	s_waitcnt lgkmcnt(1)
	v_pk_add_f32 v[0:1], v[0:1], v[98:99]
	s_waitcnt lgkmcnt(0)
	v_pk_add_f32 v[8:9], v[0:1], v[100:101]
	ds_read2st64_b32 v[0:1], v89 offset0:58 offset1:59
	ds_read2st64_b32 v[2:3], v89 offset0:90 offset1:91
	ds_read2st64_b32 v[4:5], v89 offset0:122 offset1:123
	ds_read2st64_b32 v[6:7], v89 offset0:154 offset1:155
	ds_read2st64_b32 v[96:97], v89 offset0:186 offset1:187
	ds_read2st64_b32 v[98:99], v89 offset0:218 offset1:219
	ds_read2st64_b32 v[100:101], v89 offset0:250 offset1:251
	s_waitcnt lgkmcnt(6)
	v_pk_add_f32 v[0:1], v[10:11], v[0:1]
	s_waitcnt lgkmcnt(5)
	v_pk_add_f32 v[0:1], v[0:1], v[2:3]
	s_waitcnt lgkmcnt(4)
	v_pk_add_f32 v[0:1], v[0:1], v[4:5]
	s_waitcnt lgkmcnt(3)
	v_pk_add_f32 v[0:1], v[0:1], v[6:7]
	s_waitcnt lgkmcnt(2)
	v_pk_add_f32 v[0:1], v[0:1], v[96:97]
	s_waitcnt lgkmcnt(1)
	v_pk_add_f32 v[0:1], v[0:1], v[98:99]
	s_waitcnt lgkmcnt(0)
	v_pk_add_f32 v[10:11], v[0:1], v[100:101]
	ds_read2st64_b32 v[0:1], v89 offset0:60 offset1:61
	ds_read2st64_b32 v[2:3], v89 offset0:92 offset1:93
	ds_read2st64_b32 v[4:5], v89 offset0:124 offset1:125
	ds_read2st64_b32 v[6:7], v89 offset0:156 offset1:157
	ds_read2st64_b32 v[96:97], v89 offset0:188 offset1:189
	ds_read2st64_b32 v[98:99], v89 offset0:220 offset1:221
	ds_read2st64_b32 v[100:101], v89 offset0:252 offset1:253
	s_waitcnt lgkmcnt(6)
	v_pk_add_f32 v[0:1], v[12:13], v[0:1]
	s_waitcnt lgkmcnt(5)
	v_pk_add_f32 v[0:1], v[0:1], v[2:3]
	s_waitcnt lgkmcnt(4)
	v_pk_add_f32 v[0:1], v[0:1], v[4:5]
	s_waitcnt lgkmcnt(3)
	v_pk_add_f32 v[0:1], v[0:1], v[6:7]
	s_waitcnt lgkmcnt(2)
	v_pk_add_f32 v[0:1], v[0:1], v[96:97]
	s_waitcnt lgkmcnt(1)
	v_pk_add_f32 v[0:1], v[0:1], v[98:99]
	s_waitcnt lgkmcnt(0)
	v_pk_add_f32 v[12:13], v[0:1], v[100:101]
	ds_read2st64_b32 v[0:1], v89 offset0:62 offset1:63
	ds_read2st64_b32 v[2:3], v89 offset0:94 offset1:95
	ds_read2st64_b32 v[4:5], v89 offset0:126 offset1:127
	ds_read2st64_b32 v[6:7], v89 offset0:158 offset1:159
	ds_read2st64_b32 v[72:73], v89 offset0:190 offset1:191
	ds_read2st64_b32 v[74:75], v89 offset0:222 offset1:223
	ds_read2st64_b32 v[76:77], v89 offset0:254 offset1:255
	s_waitcnt lgkmcnt(6)
	v_pk_add_f32 v[0:1], v[14:15], v[0:1]
	s_waitcnt lgkmcnt(5)
	v_pk_add_f32 v[0:1], v[0:1], v[2:3]
	s_waitcnt lgkmcnt(4)
	v_pk_add_f32 v[0:1], v[0:1], v[4:5]
	s_waitcnt lgkmcnt(3)
	v_pk_add_f32 v[0:1], v[0:1], v[6:7]
	s_waitcnt lgkmcnt(2)
	v_pk_add_f32 v[0:1], v[0:1], v[72:73]
	s_waitcnt lgkmcnt(1)
	v_pk_add_f32 v[0:1], v[0:1], v[74:75]
	s_waitcnt lgkmcnt(0)
	v_pk_add_f32 v[14:15], v[0:1], v[76:77]
	s_cbranch_vccz .LBB0_327
	s_mov_b64 s[0:1], 0x80000
	s_branch .LBB0_328
